# barrier exit-latency trim: spin-poll loops of the grid/XCD barriers without s_sleep (37 sites), otherwise identical to the pipelined-GEMV version
# speedup vs baseline: 1.0043x; 1.0043x over previous
.LBB0_73:
	global_load_dword v2, v0, s[2:3] offset:32 sc1
	s_waitcnt vmcnt(0)
	v_and_b32_e32 v2, 0xffff0000, v2
	v_cmp_ne_u32_e32 vcc, v2, v1
	s_or_b64 s[6:7], vcc, s[6:7]
	s_andn2_b64 exec, exec, s[6:7]
	s_cbranch_execnz .LBB0_73

.LBB0_176:
	v_readlane_b32 s30, v253, 12
	v_readlane_b32 s31, v253, 13
	v_readlane_b32 s7, v253, 9
	s_mov_b64 s[38:39], -1
	s_mov_b64 s[40:41], -1
	s_waitcnt lgkmcnt(0)
	s_nop 0
	global_load_dword v0, v129, s[30:31] sc1
	v_readlane_b32 s30, v253, 14
	v_readlane_b32 s31, v253, 15
	s_nop 4
	global_load_dword v1, v129, s[30:31] sc1
	v_readlane_b32 s30, v253, 16
	v_readlane_b32 s31, v253, 17
	s_waitcnt vmcnt(0)
	v_add_u32_e32 v16, v1, v0
	s_nop 2
	global_load_dword v2, v129, s[30:31] sc1
	v_readlane_b32 s30, v253, 18
	v_readlane_b32 s31, v253, 19
	s_waitcnt vmcnt(0)
	v_add_u32_e32 v16, v16, v2
	s_nop 2
	global_load_dword v3, v129, s[30:31] sc1
	v_readlane_b32 s30, v253, 20
	v_readlane_b32 s31, v253, 21
	s_waitcnt vmcnt(0)
	v_add_u32_e32 v16, v16, v3
	s_nop 2
	global_load_dword v4, v129, s[30:31] sc1
	v_readlane_b32 s30, v253, 22
	v_readlane_b32 s31, v253, 23
	s_waitcnt vmcnt(0)
	v_add_u32_e32 v16, v16, v4
	s_nop 2
	global_load_dword v5, v129, s[30:31] sc1
	v_readlane_b32 s30, v253, 24
	v_readlane_b32 s31, v253, 25
	s_waitcnt vmcnt(0)
	v_add_u32_e32 v16, v16, v5
	s_nop 2
	global_load_dword v6, v129, s[30:31] sc1
	v_readlane_b32 s30, v253, 26
	v_readlane_b32 s31, v253, 27
	s_waitcnt vmcnt(0)
	v_add_u32_e32 v16, v16, v6
	s_nop 2
	global_load_dword v7, v129, s[30:31] sc1
	v_readlane_b32 s30, v253, 28
	v_readlane_b32 s31, v253, 29
	s_waitcnt vmcnt(0)
	v_add_u32_e32 v16, v16, v7
	s_nop 2
	global_load_dword v8, v129, s[30:31] sc1
	v_readlane_b32 s30, v253, 30
	v_readlane_b32 s31, v253, 31
	s_waitcnt vmcnt(0)
	v_add_u32_e32 v16, v16, v8
	s_nop 2
	global_load_dword v9, v129, s[30:31] sc1
	v_readlane_b32 s30, v253, 32
	v_readlane_b32 s31, v253, 33
	s_waitcnt vmcnt(0)
	v_add_u32_e32 v16, v16, v9
	s_nop 2
	global_load_dword v10, v129, s[30:31] sc1
	v_readlane_b32 s30, v253, 34
	v_readlane_b32 s31, v253, 35
	s_waitcnt vmcnt(0)
	v_add_u32_e32 v16, v16, v10
	s_nop 2
	global_load_dword v11, v129, s[30:31] sc1
	v_readlane_b32 s30, v253, 36
	v_readlane_b32 s31, v253, 37
	s_waitcnt vmcnt(0)
	v_add_u32_e32 v16, v16, v11
	s_nop 2
	global_load_dword v12, v129, s[30:31] sc1
	v_readlane_b32 s30, v253, 38
	v_readlane_b32 s31, v253, 39
	s_waitcnt vmcnt(0)
	v_add_u32_e32 v16, v16, v12
	s_nop 2
	global_load_dword v13, v129, s[30:31] sc1
	v_readlane_b32 s30, v253, 40
	v_readlane_b32 s31, v253, 41
	s_waitcnt vmcnt(0)
	v_add_u32_e32 v16, v16, v13
	s_nop 2
	global_load_dword v14, v129, s[30:31] sc1
	v_readlane_b32 s30, v253, 42
	v_readlane_b32 s31, v253, 43
	s_waitcnt vmcnt(0)
	v_add_u32_e32 v16, v16, v14
	s_nop 2
	global_load_dword v15, v129, s[30:31] sc1
	s_waitcnt vmcnt(0)
	v_add_u32_e32 v16, v16, v15
	v_cmp_eq_u32_e32 vcc, s7, v16
	s_cbranch_vccnz .LBB0_175
	s_and_b32 s7, s6, 0xff
	s_cmp_eq_u32 s7, 0
	s_mov_b64 s[42:43], -1
	s_cbranch_scc1 .LBB0_180
	s_and_b64 vcc, exec, s[42:43]
	s_cbranch_vccz .LBB0_175

.LBB0_194:
	s_and_b32 s7, s6, 0xff
	s_mov_b64 s[46:47], -1
	s_cmp_lg_u32 s7, 0
	s_mov_b64 s[50:51], -1
	s_cbranch_scc0 .LBB0_197
	s_and_b64 vcc, exec, s[50:51]
	s_cbranch_vccz .LBB0_193

.LBB0_1061:
	v_readlane_b32 s30, v253, 12
	v_readlane_b32 s31, v253, 13
	v_readlane_b32 s7, v253, 9
	s_mov_b64 s[38:39], -1
	s_mov_b64 s[40:41], -1
	s_waitcnt lgkmcnt(0)
	s_nop 0
	global_load_dword v0, v129, s[30:31] sc1
	v_readlane_b32 s30, v253, 14
	v_readlane_b32 s31, v253, 15
	s_nop 4
	global_load_dword v1, v129, s[30:31] sc1
	v_readlane_b32 s30, v253, 16
	v_readlane_b32 s31, v253, 17
	s_waitcnt vmcnt(0)
	v_add_u32_e32 v16, v1, v0
	s_nop 2
	global_load_dword v2, v129, s[30:31] sc1
	v_readlane_b32 s30, v253, 18
	v_readlane_b32 s31, v253, 19
	s_waitcnt vmcnt(0)
	v_add_u32_e32 v16, v16, v2
	s_nop 2
	global_load_dword v3, v129, s[30:31] sc1
	v_readlane_b32 s30, v253, 20
	v_readlane_b32 s31, v253, 21
	s_waitcnt vmcnt(0)
	v_add_u32_e32 v16, v16, v3
	s_nop 2
	global_load_dword v4, v129, s[30:31] sc1
	v_readlane_b32 s30, v253, 22
	v_readlane_b32 s31, v253, 23
	s_waitcnt vmcnt(0)
	v_add_u32_e32 v16, v16, v4
	s_nop 2
	global_load_dword v5, v129, s[30:31] sc1
	v_readlane_b32 s30, v253, 24
	v_readlane_b32 s31, v253, 25
	s_waitcnt vmcnt(0)
	v_add_u32_e32 v16, v16, v5
	s_nop 2
	global_load_dword v6, v129, s[30:31] sc1
	v_readlane_b32 s30, v253, 26
	v_readlane_b32 s31, v253, 27
	s_waitcnt vmcnt(0)
	v_add_u32_e32 v16, v16, v6
	s_nop 2
	global_load_dword v7, v129, s[30:31] sc1
	v_readlane_b32 s30, v253, 28
	v_readlane_b32 s31, v253, 29
	s_waitcnt vmcnt(0)
	v_add_u32_e32 v16, v16, v7
	s_nop 2
	global_load_dword v8, v129, s[30:31] sc1
	v_readlane_b32 s30, v253, 30
	v_readlane_b32 s31, v253, 31
	s_waitcnt vmcnt(0)
	v_add_u32_e32 v16, v16, v8
	s_nop 2
	global_load_dword v9, v129, s[30:31] sc1
	v_readlane_b32 s30, v253, 32
	v_readlane_b32 s31, v253, 33
	s_waitcnt vmcnt(0)
	v_add_u32_e32 v16, v16, v9
	s_nop 2
	global_load_dword v10, v129, s[30:31] sc1
	v_readlane_b32 s30, v253, 34
	v_readlane_b32 s31, v253, 35
	s_waitcnt vmcnt(0)
	v_add_u32_e32 v16, v16, v10
	s_nop 2
	global_load_dword v11, v129, s[30:31] sc1
	v_readlane_b32 s30, v253, 36
	v_readlane_b32 s31, v253, 37
	s_waitcnt vmcnt(0)
	v_add_u32_e32 v16, v16, v11
	s_nop 2
	global_load_dword v12, v129, s[30:31] sc1
	v_readlane_b32 s30, v253, 38
	v_readlane_b32 s31, v253, 39
	s_waitcnt vmcnt(0)
	v_add_u32_e32 v16, v16, v12
	s_nop 2
	global_load_dword v13, v129, s[30:31] sc1
	v_readlane_b32 s30, v253, 40
	v_readlane_b32 s31, v253, 41
	s_waitcnt vmcnt(0)
	v_add_u32_e32 v16, v16, v13
	s_nop 2
	global_load_dword v14, v129, s[30:31] sc1
	v_readlane_b32 s30, v253, 42
	v_readlane_b32 s31, v253, 43
	s_waitcnt vmcnt(0)
	v_add_u32_e32 v16, v16, v14
	s_nop 2
	global_load_dword v15, v129, s[30:31] sc1
	s_waitcnt vmcnt(0)
	v_add_u32_e32 v16, v16, v15
	v_cmp_eq_u32_e32 vcc, s7, v16
	s_cbranch_vccnz .LBB0_1060
	s_and_b32 s7, s6, 0xff
	s_cmp_eq_u32 s7, 0
	s_mov_b64 s[44:45], -1
	s_cbranch_scc1 .LBB0_1065
	s_and_b64 vcc, exec, s[44:45]
	s_cbranch_vccz .LBB0_1060

.LBB0_1079:
	s_and_b32 s7, s6, 0xff
	s_mov_b64 s[48:49], -1
	s_cmp_lg_u32 s7, 0
	s_mov_b64 s[52:53], -1
	s_cbranch_scc0 .LBB0_1082
	s_and_b64 vcc, exec, s[52:53]
	s_cbranch_vccz .LBB0_1078

.LBB0_1164:
	v_readlane_b32 s30, v253, 12
	v_readlane_b32 s31, v253, 13
	v_readlane_b32 s7, v253, 9
	s_mov_b64 s[38:39], -1
	s_mov_b64 s[42:43], -1
	s_waitcnt lgkmcnt(0)
	s_nop 0
	global_load_dword v0, v129, s[30:31] sc1
	v_readlane_b32 s30, v253, 14
	v_readlane_b32 s31, v253, 15
	s_nop 4
	global_load_dword v1, v129, s[30:31] sc1
	v_readlane_b32 s30, v253, 16
	v_readlane_b32 s31, v253, 17
	s_waitcnt vmcnt(0)
	v_add_u32_e32 v16, v1, v0
	s_nop 2
	global_load_dword v2, v129, s[30:31] sc1
	v_readlane_b32 s30, v253, 18
	v_readlane_b32 s31, v253, 19
	s_waitcnt vmcnt(0)
	v_add_u32_e32 v16, v16, v2
	s_nop 2
	global_load_dword v3, v129, s[30:31] sc1
	v_readlane_b32 s30, v253, 20
	v_readlane_b32 s31, v253, 21
	s_waitcnt vmcnt(0)
	v_add_u32_e32 v16, v16, v3
	s_nop 2
	global_load_dword v4, v129, s[30:31] sc1
	v_readlane_b32 s30, v253, 22
	v_readlane_b32 s31, v253, 23
	s_waitcnt vmcnt(0)
	v_add_u32_e32 v16, v16, v4
	s_nop 2
	global_load_dword v5, v129, s[30:31] sc1
	v_readlane_b32 s30, v253, 24
	v_readlane_b32 s31, v253, 25
	s_waitcnt vmcnt(0)
	v_add_u32_e32 v16, v16, v5
	s_nop 2
	global_load_dword v6, v129, s[30:31] sc1
	v_readlane_b32 s30, v253, 26
	v_readlane_b32 s31, v253, 27
	s_waitcnt vmcnt(0)
	v_add_u32_e32 v16, v16, v6
	s_nop 2
	global_load_dword v7, v129, s[30:31] sc1
	v_readlane_b32 s30, v253, 28
	v_readlane_b32 s31, v253, 29
	s_waitcnt vmcnt(0)
	v_add_u32_e32 v16, v16, v7
	s_nop 2
	global_load_dword v8, v129, s[30:31] sc1
	v_readlane_b32 s30, v253, 30
	v_readlane_b32 s31, v253, 31
	s_waitcnt vmcnt(0)
	v_add_u32_e32 v16, v16, v8
	s_nop 2
	global_load_dword v9, v129, s[30:31] sc1
	v_readlane_b32 s30, v253, 32
	v_readlane_b32 s31, v253, 33
	s_waitcnt vmcnt(0)
	v_add_u32_e32 v16, v16, v9
	s_nop 2
	global_load_dword v10, v129, s[30:31] sc1
	v_readlane_b32 s30, v253, 34
	v_readlane_b32 s31, v253, 35
	s_waitcnt vmcnt(0)
	v_add_u32_e32 v16, v16, v10
	s_nop 2
	global_load_dword v11, v129, s[30:31] sc1
	v_readlane_b32 s30, v253, 36
	v_readlane_b32 s31, v253, 37
	s_waitcnt vmcnt(0)
	v_add_u32_e32 v16, v16, v11
	s_nop 2
	global_load_dword v12, v129, s[30:31] sc1
	v_readlane_b32 s30, v253, 38
	v_readlane_b32 s31, v253, 39
	s_waitcnt vmcnt(0)
	v_add_u32_e32 v16, v16, v12
	s_nop 2
	global_load_dword v13, v129, s[30:31] sc1
	v_readlane_b32 s30, v253, 40
	v_readlane_b32 s31, v253, 41
	s_waitcnt vmcnt(0)
	v_add_u32_e32 v16, v16, v13
	s_nop 2
	global_load_dword v14, v129, s[30:31] sc1
	v_readlane_b32 s30, v253, 42
	v_readlane_b32 s31, v253, 43
	s_waitcnt vmcnt(0)
	v_add_u32_e32 v16, v16, v14
	s_nop 2
	global_load_dword v15, v129, s[30:31] sc1
	s_waitcnt vmcnt(0)
	v_add_u32_e32 v16, v16, v15
	v_cmp_eq_u32_e32 vcc, s7, v16
	s_cbranch_vccnz .LBB0_1163
	s_and_b32 s7, s6, 0xff
	s_cmp_eq_u32 s7, 0
	s_mov_b64 s[44:45], -1
	s_cbranch_scc1 .LBB0_1168
	s_and_b64 vcc, exec, s[44:45]
	s_cbranch_vccz .LBB0_1163

.LBB0_1305:
	v_readlane_b32 s30, v253, 12
	v_readlane_b32 s31, v253, 13
	v_readlane_b32 s7, v253, 9
	s_mov_b64 s[42:43], -1
	s_mov_b64 s[44:45], -1
	s_waitcnt lgkmcnt(0)
	s_nop 0
	global_load_dword v0, v129, s[30:31] sc1
	v_readlane_b32 s30, v253, 14
	v_readlane_b32 s31, v253, 15
	s_nop 4
	global_load_dword v1, v129, s[30:31] sc1
	v_readlane_b32 s30, v253, 16
	v_readlane_b32 s31, v253, 17
	s_waitcnt vmcnt(0)
	v_add_u32_e32 v16, v1, v0
	s_nop 2
	global_load_dword v2, v129, s[30:31] sc1
	v_readlane_b32 s30, v253, 18
	v_readlane_b32 s31, v253, 19
	s_waitcnt vmcnt(0)
	v_add_u32_e32 v16, v16, v2
	s_nop 2
	global_load_dword v3, v129, s[30:31] sc1
	v_readlane_b32 s30, v253, 20
	v_readlane_b32 s31, v253, 21
	s_waitcnt vmcnt(0)
	v_add_u32_e32 v16, v16, v3
	s_nop 2
	global_load_dword v4, v129, s[30:31] sc1
	v_readlane_b32 s30, v253, 22
	v_readlane_b32 s31, v253, 23
	s_waitcnt vmcnt(0)
	v_add_u32_e32 v16, v16, v4
	s_nop 2
	global_load_dword v5, v129, s[30:31] sc1
	v_readlane_b32 s30, v253, 24
	v_readlane_b32 s31, v253, 25
	s_waitcnt vmcnt(0)
	v_add_u32_e32 v16, v16, v5
	s_nop 2
	global_load_dword v6, v129, s[30:31] sc1
	v_readlane_b32 s30, v253, 26
	v_readlane_b32 s31, v253, 27
	s_waitcnt vmcnt(0)
	v_add_u32_e32 v16, v16, v6
	s_nop 2
	global_load_dword v7, v129, s[30:31] sc1
	v_readlane_b32 s30, v253, 28
	v_readlane_b32 s31, v253, 29
	s_waitcnt vmcnt(0)
	v_add_u32_e32 v16, v16, v7
	s_nop 2
	global_load_dword v8, v129, s[30:31] sc1
	v_readlane_b32 s30, v253, 30
	v_readlane_b32 s31, v253, 31
	s_waitcnt vmcnt(0)
	v_add_u32_e32 v16, v16, v8
	s_nop 2
	global_load_dword v9, v129, s[30:31] sc1
	v_readlane_b32 s30, v253, 32
	v_readlane_b32 s31, v253, 33
	s_waitcnt vmcnt(0)
	v_add_u32_e32 v16, v16, v9
	s_nop 2
	global_load_dword v10, v129, s[30:31] sc1
	v_readlane_b32 s30, v253, 34
	v_readlane_b32 s31, v253, 35
	s_waitcnt vmcnt(0)
	v_add_u32_e32 v16, v16, v10
	s_nop 2
	global_load_dword v11, v129, s[30:31] sc1
	v_readlane_b32 s30, v253, 36
	v_readlane_b32 s31, v253, 37
	s_waitcnt vmcnt(0)
	v_add_u32_e32 v16, v16, v11
	s_nop 2
	global_load_dword v12, v129, s[30:31] sc1
	v_readlane_b32 s30, v253, 38
	v_readlane_b32 s31, v253, 39
	s_waitcnt vmcnt(0)
	v_add_u32_e32 v16, v16, v12
	s_nop 2
	global_load_dword v13, v129, s[30:31] sc1
	v_readlane_b32 s30, v253, 40
	v_readlane_b32 s31, v253, 41
	s_waitcnt vmcnt(0)
	v_add_u32_e32 v16, v16, v13
	s_nop 2
	global_load_dword v14, v129, s[30:31] sc1
	v_readlane_b32 s30, v253, 42
	v_readlane_b32 s31, v253, 43
	s_waitcnt vmcnt(0)
	v_add_u32_e32 v16, v16, v14
	s_nop 2
	global_load_dword v15, v129, s[30:31] sc1
	s_waitcnt vmcnt(0)
	v_add_u32_e32 v16, v16, v15
	v_cmp_eq_u32_e32 vcc, s7, v16
	s_cbranch_vccnz .LBB0_1304
	s_and_b32 s7, s6, 0xff
	s_cmp_eq_u32 s7, 0
	s_mov_b64 s[46:47], -1
	s_cbranch_scc1 .LBB0_1309
	s_and_b64 vcc, exec, s[46:47]
	s_cbranch_vccz .LBB0_1304

.LBB0_1323:
	s_and_b32 s7, s6, 0xff
	s_mov_b64 s[50:51], -1
	s_cmp_lg_u32 s7, 0
	s_mov_b64 s[54:55], -1
	s_cbranch_scc0 .LBB0_1326
	s_and_b64 vcc, exec, s[54:55]
	s_cbranch_vccz .LBB0_1322
